# P0 row pass: L2 prefetch of the next iteration's two rows (one dword per 128-B line), counted waits +1
# baseline (speedup 1.0000x reference)
.LBB0_47:
	v_readlane_b32 s32, v254, 6
	v_lshlrev_b32_e32 v60, 3, v34
	v_and_b32_e32 v60, 0xfff, v60
	s_add_i32 s26, s19, s32
	s_add_i32 s27, s26, s32
	s_cmp_lt_i32 s26, 0x8080
	s_cselect_b32 s26, s26, s4
	s_cmp_lt_i32 s27, 0x8080
	s_cselect_b32 s27, s27, s4
	s_cmp_lt_i32 s26, 0x8000
	s_cselect_b32 s28, s36, s38
	s_cselect_b32 s29, s37, s39
	s_and_b32 s26, s26, 0x7fff
	s_lshl_b32 s26, s26, 12
	s_add_u32 s28, s28, s26
	s_addc_u32 s29, s29, 0
	s_cmp_lt_i32 s27, 0x8000
	s_cselect_b32 s30, s36, s38
	s_cselect_b32 s31, s37, s39
	s_and_b32 s27, s27, 0x7fff
	s_lshl_b32 s27, s27, 12
	s_add_u32 s30, s30, s27
	s_addc_u32 s31, s31, 0
	v_cmp_gt_u32_e32 vcc, 0x200, v34
	v_mov_b32_e32 v66, s30
	v_mov_b32_e32 v67, s31
	v_mov_b32_e32 v63, s28
	v_mov_b32_e32 v64, s29
	v_cndmask_b32_e32 v66, v66, v63, vcc
	v_cndmask_b32_e32 v67, v67, v64, vcc
	v_add_co_u32_e32 v66, vcc, v66, v60
	s_nop 1
	v_addc_co_u32_e32 v67, vcc, 0, v67, vcc
	global_load_dword v63, v[66:67], off
	s_waitcnt vmcnt(4)
	v_pk_mul_f32 v[38:39], v[28:29], v[28:29]
	v_pk_mul_f32 v[40:41], v[26:27], v[26:27]
	v_mov_b32_e32 v43, v39
	v_mov_b32_e32 v42, v40
	v_pk_mov_b32 v[38:39], v[40:41], v[38:39] op_sel:[1,0]
	v_pk_mul_f32 v[40:41], v[18:19], v[18:19]
	v_pk_add_f32 v[38:39], v[38:39], v[42:43]
	v_pk_mul_f32 v[42:43], v[20:21], v[20:21]
	v_mov_b32_e32 v44, v40
	v_mov_b32_e32 v45, v43
	v_pk_mov_b32 v[40:41], v[40:41], v[42:43] op_sel:[1,0]
	s_waitcnt vmcnt(3)
	v_pk_mul_f32 v[42:43], v[32:33], v[32:33]
	v_pk_add_f32 v[40:41], v[40:41], v[44:45]
	v_pk_mul_f32 v[44:45], v[30:31], v[30:31]
	v_mov_b32_e32 v55, v43
	v_mov_b32_e32 v54, v44
	v_pk_mov_b32 v[42:43], v[44:45], v[42:43] op_sel:[1,0]
	v_pk_mul_f32 v[44:45], v[6:7], v[6:7]
	v_pk_add_f32 v[42:43], v[42:43], v[54:55]
	v_pk_mul_f32 v[54:55], v[8:9], v[8:9]
	v_mov_b32_e32 v56, v44
	v_pk_mov_b32 v[44:45], v[44:45], v[54:55] op_sel:[1,0]
	s_waitcnt vmcnt(1)
	v_mul_f32_e32 v53, v14, v14
	v_mul_f32_e32 v54, v15, v15
	v_pk_add_f32 v[38:39], v[38:39], v[38:39] op_sel:[0,1] op_sel_hi:[1,0]
	v_pk_add_f32 v[42:43], v[42:43], v[42:43] op_sel:[0,1] op_sel_hi:[1,0]
	v_mov_b32_e32 v39, v53
	v_mov_b32_e32 v43, v54
	v_pk_add_f32 v[38:39], v[38:39], v[42:43]
	v_mul_f32_e32 v42, v23, v23
	v_mov_b32_e32 v57, v55
	v_mul_f32_e32 v55, v16, v16
	v_pk_fma_f32 v[42:43], v[22:23], v[22:23], v[42:43] op_sel_hi:[1,1,0]
	v_mul_f32_e32 v54, v25, v25
	v_pk_add_f32 v[44:45], v[44:45], v[56:57]
	v_mul_f32_e32 v56, v17, v17
	v_mov_b32_e32 v43, v55
	v_pk_fma_f32 v[54:55], v[24:25], v[24:25], v[54:55] op_sel_hi:[1,1,0]
	s_lshl_b64 s[20:21], s[4:5], 11
	v_mov_b32_e32 v55, v56
	v_pk_add_f32 v[42:43], v[42:43], v[54:55]
	v_mul_f32_e32 v54, v4, v4
	v_pk_add_f32 v[38:39], v[38:39], v[42:43]
	v_mul_f32_e32 v42, v2, v2
	v_add_f32_e32 v53, v38, v39
	v_pk_add_f32 v[38:39], v[40:41], v[40:41] op_sel:[0,1] op_sel_hi:[1,0]
	v_pk_add_f32 v[40:41], v[44:45], v[44:45] op_sel:[0,1] op_sel_hi:[1,0]
	ds_bpermute_b32 v44, v1, v53
	v_mul_f32_e32 v43, v3, v3
	v_mov_b32_e32 v39, v42
	v_mov_b32_e32 v41, v43
	v_pk_add_f32 v[38:39], v[38:39], v[40:41]
	s_waitcnt lgkmcnt(0)
	v_add_f32_e32 v44, v53, v44
	ds_bpermute_b32 v45, v46, v44
	v_mul_f32_e32 v40, v11, v11
	v_mul_f32_e32 v42, v13, v13
	v_mul_f32_e32 v55, v5, v5
	v_pk_fma_f32 v[40:41], v[10:11], v[10:11], v[40:41] op_sel_hi:[1,1,0]
	v_pk_fma_f32 v[42:43], v[12:13], v[12:13], v[42:43] op_sel_hi:[1,1,0]
	v_mov_b32_e32 v41, v54
	v_mov_b32_e32 v43, v55
	v_pk_add_f32 v[40:41], v[40:41], v[42:43]
	s_lshl_b64 s[22:23], s[14:15], 11
	v_pk_add_f32 v[38:39], v[38:39], v[40:41]
	s_waitcnt lgkmcnt(0)
	v_add_f32_e32 v40, v44, v45
	ds_bpermute_b32 v41, v47, v40
	v_add_f32_e32 v38, v38, v39
	ds_bpermute_b32 v39, v1, v38
	s_waitcnt lgkmcnt(1)
	v_add_f32_e32 v40, v40, v41
	ds_bpermute_b32 v41, v48, v40
	s_waitcnt lgkmcnt(1)
	v_add_f32_e32 v38, v38, v39
	ds_bpermute_b32 v39, v46, v38
	s_waitcnt lgkmcnt(1)
	v_add_f32_e32 v40, v40, v41
	ds_bpermute_b32 v41, v49, v40
	s_waitcnt lgkmcnt(1)
	v_add_f32_e32 v38, v38, v39
	ds_bpermute_b32 v39, v47, v38
	s_waitcnt lgkmcnt(1)
	v_add_f32_e32 v40, v40, v41
	ds_bpermute_b32 v41, v50, v40
	s_waitcnt lgkmcnt(1)
	v_add_f32_e32 v38, v38, v39
	ds_bpermute_b32 v39, v48, v38
	s_waitcnt lgkmcnt(1)
	v_add_f32_e32 v40, v40, v41
	v_fmamk_f32 v40, v40, 0x3a800000, v51
	v_mul_f32_e32 v41, 0x4f800000, v40
	v_cmp_gt_f32_e32 vcc, s18, v40
	s_waitcnt lgkmcnt(0)
	v_add_f32_e32 v38, v38, v39
	ds_bpermute_b32 v39, v49, v38
	v_cndmask_b32_e32 v40, v40, v41, vcc
	v_sqrt_f32_e32 v41, v40
	s_waitcnt lgkmcnt(0)
	v_add_f32_e32 v38, v38, v39
	v_add_u32_e32 v42, -1, v41
	v_fma_f32 v43, -v42, v41, v40
	v_cmp_ge_f32_e64 s[8:9], 0, v43
	v_add_u32_e32 v43, 1, v41
	ds_bpermute_b32 v39, v50, v38
	v_cndmask_b32_e64 v42, v41, v42, s[8:9]
	v_fma_f32 v41, -v43, v41, v40
	v_cmp_lt_f32_e64 s[8:9], 0, v41
	s_waitcnt lgkmcnt(0)
	v_add_f32_e32 v38, v38, v39
	v_cndmask_b32_e64 v41, v42, v43, s[8:9]
	v_mul_f32_e32 v42, 0x37800000, v41
	v_cndmask_b32_e32 v41, v41, v42, vcc
	v_cmp_class_f32_e32 vcc, v40, v52
	v_fmamk_f32 v38, v38, 0x3a800000, v51
	v_mul_f32_e32 v44, 0x4f800000, v38
	v_cndmask_b32_e32 v40, v41, v40, vcc
	v_div_scale_f32 v41, s[8:9], v40, v40, 1.0
	v_rcp_f32_e32 v42, v41
	v_cmp_gt_f32_e64 s[8:9], s18, v38
	v_fma_f32 v39, -v41, v42, 1.0
	s_nop 0
	v_cndmask_b32_e64 v38, v38, v44, s[8:9]
	v_fmac_f32_e32 v42, v39, v42
	v_div_scale_f32 v39, vcc, 1.0, v40, 1.0
	v_sqrt_f32_e32 v44, v38
	v_mul_f32_e32 v43, v39, v42
	v_fma_f32 v45, -v41, v43, v39
	v_fmac_f32_e32 v43, v45, v42
	v_fma_f32 v39, -v41, v43, v39
	v_add_u32_e32 v41, -1, v44
	v_fma_f32 v45, -v41, v44, v38
	v_cmp_ge_f32_e64 s[10:11], 0, v45
	v_add_u32_e32 v45, 1, v44
	s_nop 0
	v_cndmask_b32_e64 v41, v44, v41, s[10:11]
	v_fma_f32 v44, -v45, v44, v38
	v_cmp_lt_f32_e64 s[10:11], 0, v44
	s_nop 1
	v_cndmask_b32_e64 v41, v41, v45, s[10:11]
	v_mul_f32_e32 v44, 0x37800000, v41
	v_cndmask_b32_e64 v41, v41, v44, s[8:9]
	v_cmp_class_f32_e64 s[8:9], v38, v52
	s_nop 1
	v_cndmask_b32_e64 v41, v41, v38, s[8:9]
	v_div_scale_f32 v44, s[8:9], v41, v41, 1.0
	v_rcp_f32_e32 v45, v44
	v_div_fmas_f32 v38, v39, v42, v43
	v_div_fixup_f32 v38, v38, v40, 1.0
	v_fma_f32 v39, -v44, v45, 1.0
	v_fmac_f32_e32 v45, v39, v45
	v_div_scale_f32 v39, vcc, 1.0, v41, 1.0
	v_mul_f32_e32 v40, v39, v45
	v_fma_f32 v42, -v44, v40, v39
	v_fmac_f32_e32 v40, v42, v45
	v_fma_f32 v39, -v44, v40, v39
	v_div_fmas_f32 v39, v39, v45, v40
	v_div_fixup_f32 v40, v39, v41, 1.0
	v_pk_mul_f32 v[28:29], v[28:29], v[38:39] op_sel_hi:[1,0]
	v_pk_mul_f32 v[26:27], v[26:27], v[38:39] op_sel_hi:[1,0]
	v_lshl_add_u64 v[44:45], v[36:37], 0, s[20:21]
	v_lshl_add_u64 v[42:43], v[36:37], 0, s[22:23]
	v_mov_b32_e32 v41, v40
	v_cvt_pk_bf16_f32 v26, v26, v27
	v_cvt_pk_bf16_f32 v27, v28, v29
	s_and_b64 vcc, exec, s[6:7]
	global_store_dwordx2 v[44:45], v[26:27], off
	s_cbranch_vccnz .LBB0_49
	v_mov_b32_e32 v26, v40
	v_mov_b32_e32 v27, v40
	v_pk_mul_f32 v[20:21], v[20:21], v[26:27]
	v_pk_mul_f32 v[18:19], v[18:19], v[40:41]
	s_nop 0
	v_cvt_pk_bf16_f32 v18, v18, v19
	v_cvt_pk_bf16_f32 v19, v20, v21
	global_store_dwordx2 v[42:43], v[18:19], off
